# combo1 plus batched cos/sin loads in the rotary GEMM epilogue
# baseline (speedup 1.0000x reference)
.LBB0_222:
	v_lshlrev_b32_e32 v149, 7, v147
	v_and_b32_e32 v178, 0x3e780, v149
	v_lshl_add_u64 v[166:167], v[138:139], 0, v[178:179]
	v_lshl_add_u64 v[174:175], v[140:141], 0, v[178:179]
	v_mov_b64_e32 v[244:245], v[166:167]
	v_mov_b64_e32 v[246:247], v[174:175]
	v_mov_b64_e32 v[212:213], v[244:245]
	global_load_dwordx4 v[212:215], v[212:213], off offset:16
	v_mov_b64_e32 v[216:217], v[244:245]
	global_load_dwordx4 v[216:219], v[216:217], off
	v_mov_b64_e32 v[220:221], v[246:247]
	global_load_dwordx4 v[220:223], v[220:221], off offset:16
	v_mov_b64_e32 v[224:225], v[246:247]
	global_load_dwordx4 v[224:227], v[224:225], off
	s_mov_b32 s98, 0x800
	s_mov_b32 s99, 0
	v_lshl_add_u64 v[228:229], v[244:245], 0, s[98:99]
	global_load_dwordx4 v[228:231], v[228:229], off offset:16
	s_mov_b32 s98, 0x800
	s_mov_b32 s99, 0
	v_lshl_add_u64 v[232:233], v[244:245], 0, s[98:99]
	global_load_dwordx4 v[232:235], v[232:233], off
	s_mov_b32 s98, 0x800
	s_mov_b32 s99, 0
	v_lshl_add_u64 v[236:237], v[246:247], 0, s[98:99]
	global_load_dwordx4 v[236:239], v[236:237], off offset:16
	s_mov_b32 s98, 0x800
	s_mov_b32 s99, 0
	v_lshl_add_u64 v[240:241], v[246:247], 0, s[98:99]
	global_load_dwordx4 v[240:243], v[240:241], off
	s_waitcnt vmcnt(0)
	v_mov_b64_e32 v[162:163], v[212:213]
	v_mov_b64_e32 v[164:165], v[214:215]
	s_nop 0
	v_mov_b64_e32 v[166:167], v[216:217]
	v_mov_b64_e32 v[168:169], v[218:219]
	s_nop 0
	v_mov_b64_e32 v[170:171], v[220:221]
	v_mov_b64_e32 v[172:173], v[222:223]
	s_nop 0
	v_mov_b64_e32 v[174:175], v[224:225]
	v_mov_b64_e32 v[176:177], v[226:227]
	s_cmp_lt_i32 s28, 4
	s_cselect_b64 vcc, -1, 0
	v_cndmask_b32_e32 v148, 1.0, v201, vcc
	s_lshl_b32 s0, s28, 8
	s_ashr_i32 s1, s0, 31
	s_movk_i32 s15, 0x1800
	s_lshl_b64 s[28:29], s[0:1], 1
	v_pk_mul_f32 v[206:207], v[114:115], v[170:171]
	v_pk_mul_f32 v[198:199], v[118:119], v[174:175]
	v_pk_fma_f32 v[206:207], v[122:123], v[162:163], v[206:207] neg_lo:[0,0,1] neg_hi:[0,0,1]
	v_pk_fma_f32 v[198:199], v[126:127], v[166:167], v[198:199] neg_lo:[0,0,1] neg_hi:[0,0,1]
	v_pk_mul_f32 v[126:127], v[126:127], v[174:175]
	v_pk_mul_f32 v[122:123], v[122:123], v[170:171]
	v_pk_fma_f32 v[118:119], v[118:119], v[166:167], v[126:127]
	v_pk_mul_f32 v[202:203], v[116:117], v[172:173]
	v_pk_mul_f32 v[126:127], v[148:149], v[118:119] op_sel_hi:[0,1]
	v_pk_mul_f32 v[118:119], v[124:125], v[172:173]
	v_pk_fma_f32 v[114:115], v[114:115], v[162:163], v[122:123]
	v_pk_fma_f32 v[202:203], v[124:125], v[164:165], v[202:203] neg_lo:[0,0,1] neg_hi:[0,0,1]
	v_pk_fma_f32 v[116:117], v[116:117], v[164:165], v[118:119]
	v_pk_mul_f32 v[124:125], v[148:149], v[114:115] op_sel_hi:[0,1]
	v_mov_b64_e32 v[114:115], s[10:11]
	v_pk_mul_f32 v[122:123], v[148:149], v[116:117] op_sel_hi:[0,1]
	v_mad_i64_i32 v[116:117], s[16:17], v147, s15, v[114:115]
	v_pk_mul_f32 v[196:197], v[120:121], v[176:177]
	v_lshl_add_u64 v[116:117], v[116:117], 0, s[28:29]
	v_pk_fma_f32 v[196:197], v[128:129], v[168:169], v[196:197] neg_lo:[0,0,1] neg_hi:[0,0,1]
	v_pk_mul_f32 v[128:129], v[128:129], v[176:177]
	v_lshl_add_u64 v[116:117], v[116:117], 0, s[82:83]
	v_mov_b32_e32 v147, v179
	v_pk_mul_f32 v[198:199], v[148:149], v[198:199] op_sel_hi:[0,1]
	v_pk_fma_f32 v[120:121], v[120:121], v[168:169], v[128:129]
	v_lshl_add_u64 v[128:129], v[116:117], 0, v[146:147]
	v_cvt_pk_bf16_f32 v116, v198, v199
	v_pk_mul_f32 v[196:197], v[148:149], v[196:197] op_sel_hi:[0,1]
	v_pk_mul_f32 v[202:203], v[148:149], v[202:203] op_sel_hi:[0,1]
	v_pk_mul_f32 v[206:207], v[148:149], v[206:207] op_sel_hi:[0,1]
	v_cvt_pk_bf16_f32 v117, v196, v197
	v_cvt_pk_bf16_f32 v118, v206, v207
	v_cvt_pk_bf16_f32 v119, v202, v203
	global_store_dwordx4 v[128:129], v[116:119], off sc1
	v_pk_mul_f32 v[120:121], v[148:149], v[120:121] op_sel_hi:[0,1]
	s_nop 0
	v_cvt_pk_bf16_f32 v116, v126, v127
	v_cvt_pk_bf16_f32 v117, v120, v121
	v_cvt_pk_bf16_f32 v118, v124, v125
	v_cvt_pk_bf16_f32 v119, v122, v123
	global_store_dwordx4 v[128:129], v[116:119], off offset:64 sc1
	s_nop 1
	v_lshlrev_b32_e32 v116, 7, v160
	v_and_b32_e32 v178, 0x3ef80, v116
	v_lshl_add_u64 v[120:121], v[138:139], 0, v[178:179]
	v_lshl_add_u64 v[128:129], v[140:141], 0, v[178:179]
	v_mov_b64_e32 v[116:117], v[228:229]
	v_mov_b64_e32 v[118:119], v[230:231]
	s_nop 0
	v_mov_b64_e32 v[120:121], v[232:233]
	v_mov_b64_e32 v[122:123], v[234:235]
	s_nop 0
	v_mov_b64_e32 v[124:125], v[236:237]
	v_mov_b64_e32 v[126:127], v[238:239]
	v_mov_b64_e32 v[162:163], v[240:241]
	v_mov_b64_e32 v[164:165], v[242:243]
	s_mov_b32 s98, 0x1000
	s_mov_b32 s99, 0
	v_lshl_add_u64 v[212:213], v[244:245], 0, s[98:99]
	global_load_dwordx4 v[212:215], v[212:213], off offset:16
	s_mov_b32 s98, 0x1000
	s_mov_b32 s99, 0
	v_lshl_add_u64 v[216:217], v[244:245], 0, s[98:99]
	global_load_dwordx4 v[216:219], v[216:217], off
	s_mov_b32 s98, 0x1000
	s_mov_b32 s99, 0
	v_lshl_add_u64 v[220:221], v[246:247], 0, s[98:99]
	global_load_dwordx4 v[220:223], v[220:221], off offset:16
	s_mov_b32 s98, 0x1000
	s_mov_b32 s99, 0
	v_lshl_add_u64 v[224:225], v[246:247], 0, s[98:99]
	global_load_dwordx4 v[224:227], v[224:225], off
	s_mov_b32 s98, 0x1800
	s_mov_b32 s99, 0
	v_lshl_add_u64 v[228:229], v[244:245], 0, s[98:99]
	global_load_dwordx4 v[228:231], v[228:229], off offset:16
	s_mov_b32 s98, 0x1800
	s_mov_b32 s99, 0
	v_lshl_add_u64 v[232:233], v[244:245], 0, s[98:99]
	global_load_dwordx4 v[232:235], v[232:233], off
	s_mov_b32 s98, 0x1800
	s_mov_b32 s99, 0
	v_lshl_add_u64 v[236:237], v[246:247], 0, s[98:99]
	global_load_dwordx4 v[236:239], v[236:237], off offset:16
	s_mov_b32 s98, 0x1800
	s_mov_b32 s99, 0
	v_lshl_add_u64 v[240:241], v[246:247], 0, s[98:99]
	global_load_dwordx4 v[240:243], v[240:241], off
	v_pk_mul_f32 v[170:171], v[98:99], v[124:125]
	v_pk_mul_f32 v[168:169], v[100:101], v[126:127]
	v_pk_fma_f32 v[170:171], v[106:107], v[116:117], v[170:171] neg_lo:[0,0,1] neg_hi:[0,0,1]
	v_pk_mul_f32 v[106:107], v[106:107], v[124:125]
	v_pk_fma_f32 v[168:169], v[108:109], v[118:119], v[168:169] neg_lo:[0,0,1] neg_hi:[0,0,1]
	v_pk_mul_f32 v[108:109], v[108:109], v[126:127]
	v_pk_fma_f32 v[98:99], v[98:99], v[116:117], v[106:107]
	v_pk_fma_f32 v[100:101], v[100:101], v[118:119], v[108:109]
	v_pk_mul_f32 v[108:109], v[148:149], v[98:99] op_sel_hi:[0,1]
	v_mad_i64_i32 v[98:99], s[0:1], v160, s15, v[114:115]
	v_pk_mul_f32 v[166:167], v[102:103], v[162:163]
	v_lshl_add_u64 v[98:99], v[98:99], 0, s[28:29]
	v_pk_mul_f32 v[128:129], v[104:105], v[164:165]
	v_pk_fma_f32 v[166:167], v[110:111], v[120:121], v[166:167] neg_lo:[0,0,1] neg_hi:[0,0,1]
	v_pk_mul_f32 v[110:111], v[110:111], v[162:163]
	v_lshl_add_u64 v[98:99], v[98:99], 0, s[82:83]
	v_pk_fma_f32 v[128:129], v[112:113], v[122:123], v[128:129] neg_lo:[0,0,1] neg_hi:[0,0,1]
	v_pk_mul_f32 v[166:167], v[148:149], v[166:167] op_sel_hi:[0,1]
	v_pk_mul_f32 v[112:113], v[112:113], v[164:165]
	v_pk_fma_f32 v[102:103], v[102:103], v[120:121], v[110:111]
	v_lshl_add_u64 v[110:111], v[98:99], 0, v[146:147]
	v_cvt_pk_bf16_f32 v98, v166, v167
	v_pk_mul_f32 v[128:129], v[148:149], v[128:129] op_sel_hi:[0,1]
	v_pk_mul_f32 v[168:169], v[148:149], v[168:169] op_sel_hi:[0,1]
	v_pk_mul_f32 v[170:171], v[148:149], v[170:171] op_sel_hi:[0,1]
	v_pk_fma_f32 v[104:105], v[104:105], v[122:123], v[112:113]
	v_pk_mul_f32 v[102:103], v[148:149], v[102:103] op_sel_hi:[0,1]
	v_pk_mul_f32 v[106:107], v[148:149], v[100:101] op_sel_hi:[0,1]
	v_cvt_pk_bf16_f32 v99, v128, v129
	v_cvt_pk_bf16_f32 v100, v170, v171
	v_cvt_pk_bf16_f32 v101, v168, v169
	global_store_dwordx4 v[110:111], v[98:101], off sc1
	v_pk_mul_f32 v[104:105], v[148:149], v[104:105] op_sel_hi:[0,1]
	s_nop 0
	v_cvt_pk_bf16_f32 v98, v102, v103
	v_cvt_pk_bf16_f32 v99, v104, v105
	v_cvt_pk_bf16_f32 v100, v108, v109
	v_cvt_pk_bf16_f32 v101, v106, v107
	global_store_dwordx4 v[110:111], v[98:101], off offset:64 sc1
	s_nop 1
	v_lshlrev_b32_e32 v98, 7, v159
	v_and_b32_e32 v178, 0x3f780, v98
	v_lshl_add_u64 v[102:103], v[138:139], 0, v[178:179]
	v_lshl_add_u64 v[110:111], v[140:141], 0, v[178:179]
	s_waitcnt vmcnt(2)
	v_mov_b64_e32 v[98:99], v[212:213]
	v_mov_b64_e32 v[100:101], v[214:215]
	s_nop 0
	v_mov_b64_e32 v[102:103], v[216:217]
	v_mov_b64_e32 v[104:105], v[218:219]
	s_nop 0
	v_mov_b64_e32 v[106:107], v[220:221]
	v_mov_b64_e32 v[108:109], v[222:223]
	s_nop 0
	v_mov_b64_e32 v[110:111], v[224:225]
	v_mov_b64_e32 v[112:113], v[226:227]
	v_pk_mul_f32 v[122:123], v[82:83], v[106:107]
	v_pk_mul_f32 v[120:121], v[84:85], v[108:109]
	v_pk_fma_f32 v[122:123], v[90:91], v[98:99], v[122:123] neg_lo:[0,0,1] neg_hi:[0,0,1]
	v_pk_mul_f32 v[90:91], v[90:91], v[106:107]
	v_pk_fma_f32 v[120:121], v[92:93], v[100:101], v[120:121] neg_lo:[0,0,1] neg_hi:[0,0,1]
	v_pk_mul_f32 v[92:93], v[92:93], v[108:109]
	v_pk_fma_f32 v[82:83], v[82:83], v[98:99], v[90:91]
	v_pk_fma_f32 v[84:85], v[84:85], v[100:101], v[92:93]
	v_pk_mul_f32 v[92:93], v[148:149], v[82:83] op_sel_hi:[0,1]
	v_mad_i64_i32 v[82:83], s[0:1], v159, s15, v[114:115]
	v_pk_mul_f32 v[118:119], v[86:87], v[110:111]
	v_lshl_add_u64 v[82:83], v[82:83], 0, s[28:29]
	v_pk_mul_f32 v[116:117], v[88:89], v[112:113]
	v_pk_fma_f32 v[118:119], v[94:95], v[102:103], v[118:119] neg_lo:[0,0,1] neg_hi:[0,0,1]
	v_pk_mul_f32 v[94:95], v[94:95], v[110:111]
	v_lshl_add_u64 v[82:83], v[82:83], 0, s[82:83]
	v_pk_fma_f32 v[116:117], v[96:97], v[104:105], v[116:117] neg_lo:[0,0,1] neg_hi:[0,0,1]
	v_pk_mul_f32 v[118:119], v[148:149], v[118:119] op_sel_hi:[0,1]
	v_pk_mul_f32 v[96:97], v[96:97], v[112:113]
	v_pk_fma_f32 v[86:87], v[86:87], v[102:103], v[94:95]
	v_lshl_add_u64 v[94:95], v[82:83], 0, v[146:147]
	v_cvt_pk_bf16_f32 v82, v118, v119
	v_pk_mul_f32 v[116:117], v[148:149], v[116:117] op_sel_hi:[0,1]
	v_pk_mul_f32 v[120:121], v[148:149], v[120:121] op_sel_hi:[0,1]
	v_pk_mul_f32 v[122:123], v[148:149], v[122:123] op_sel_hi:[0,1]
	v_pk_fma_f32 v[88:89], v[88:89], v[104:105], v[96:97]
	v_pk_mul_f32 v[86:87], v[148:149], v[86:87] op_sel_hi:[0,1]
	v_pk_mul_f32 v[90:91], v[148:149], v[84:85] op_sel_hi:[0,1]
	v_cvt_pk_bf16_f32 v83, v116, v117
	v_cvt_pk_bf16_f32 v84, v122, v123
	v_cvt_pk_bf16_f32 v85, v120, v121
	global_store_dwordx4 v[94:95], v[82:85], off sc1
	v_pk_mul_f32 v[88:89], v[148:149], v[88:89] op_sel_hi:[0,1]
	s_nop 0
	v_cvt_pk_bf16_f32 v82, v86, v87
	v_cvt_pk_bf16_f32 v83, v88, v89
	v_cvt_pk_bf16_f32 v84, v92, v93
	v_cvt_pk_bf16_f32 v85, v90, v91
	global_store_dwordx4 v[94:95], v[82:85], off offset:64 sc1
	s_nop 1
	v_lshlrev_b32_e32 v82, 7, v158
	v_and_b32_e32 v178, 0x3ff80, v82
	v_lshl_add_u64 v[86:87], v[138:139], 0, v[178:179]
	v_lshl_add_u64 v[94:95], v[140:141], 0, v[178:179]
	v_mov_b64_e32 v[82:83], v[228:229]
	v_mov_b64_e32 v[84:85], v[230:231]
	s_nop 0
	v_mov_b64_e32 v[86:87], v[232:233]
	v_mov_b64_e32 v[88:89], v[234:235]
	s_nop 0
	v_mov_b64_e32 v[90:91], v[236:237]
	v_mov_b64_e32 v[92:93], v[238:239]
	s_nop 0
	v_mov_b64_e32 v[94:95], v[240:241]
	v_mov_b64_e32 v[96:97], v[242:243]
	s_mov_b32 s98, 0x4000
	s_mov_b32 s99, 0
	v_lshl_add_u64 v[212:213], v[244:245], 0, s[98:99]
	global_load_dwordx4 v[212:215], v[212:213], off offset:16
	s_mov_b32 s98, 0x4000
	s_mov_b32 s99, 0
	v_lshl_add_u64 v[216:217], v[244:245], 0, s[98:99]
	global_load_dwordx4 v[216:219], v[216:217], off
	s_mov_b32 s98, 0x4000
	s_mov_b32 s99, 0
	v_lshl_add_u64 v[220:221], v[246:247], 0, s[98:99]
	global_load_dwordx4 v[220:223], v[220:221], off offset:16
	s_mov_b32 s98, 0x4000
	s_mov_b32 s99, 0
	v_lshl_add_u64 v[224:225], v[246:247], 0, s[98:99]
	global_load_dwordx4 v[224:227], v[224:225], off
	s_mov_b32 s98, 0x4800
	s_mov_b32 s99, 0
	v_lshl_add_u64 v[228:229], v[244:245], 0, s[98:99]
	global_load_dwordx4 v[228:231], v[228:229], off offset:16
	s_mov_b32 s98, 0x4800
	s_mov_b32 s99, 0
	v_lshl_add_u64 v[232:233], v[244:245], 0, s[98:99]
	global_load_dwordx4 v[232:235], v[232:233], off
	s_mov_b32 s98, 0x4800
	s_mov_b32 s99, 0
	v_lshl_add_u64 v[236:237], v[246:247], 0, s[98:99]
	global_load_dwordx4 v[236:239], v[236:237], off offset:16
	s_mov_b32 s98, 0x4800
	s_mov_b32 s99, 0
	v_lshl_add_u64 v[240:241], v[246:247], 0, s[98:99]
	global_load_dwordx4 v[240:243], v[240:241], off
	v_pk_mul_f32 v[104:105], v[66:67], v[90:91]
	v_pk_mul_f32 v[102:103], v[68:69], v[92:93]
	v_pk_fma_f32 v[104:105], v[74:75], v[82:83], v[104:105] neg_lo:[0,0,1] neg_hi:[0,0,1]
	v_pk_mul_f32 v[74:75], v[74:75], v[90:91]
	v_pk_fma_f32 v[102:103], v[76:77], v[84:85], v[102:103] neg_lo:[0,0,1] neg_hi:[0,0,1]
	v_pk_mul_f32 v[76:77], v[76:77], v[92:93]
	v_pk_fma_f32 v[66:67], v[66:67], v[82:83], v[74:75]
	v_pk_fma_f32 v[68:69], v[68:69], v[84:85], v[76:77]
	v_pk_mul_f32 v[76:77], v[148:149], v[66:67] op_sel_hi:[0,1]
	v_mad_i64_i32 v[66:67], s[0:1], v158, s15, v[114:115]
	v_pk_mul_f32 v[100:101], v[70:71], v[94:95]
	v_lshl_add_u64 v[66:67], v[66:67], 0, s[28:29]
	v_pk_mul_f32 v[98:99], v[72:73], v[96:97]
	v_pk_fma_f32 v[100:101], v[78:79], v[86:87], v[100:101] neg_lo:[0,0,1] neg_hi:[0,0,1]
	v_pk_mul_f32 v[78:79], v[78:79], v[94:95]
	v_lshl_add_u64 v[66:67], v[66:67], 0, s[82:83]
	v_pk_fma_f32 v[98:99], v[80:81], v[88:89], v[98:99] neg_lo:[0,0,1] neg_hi:[0,0,1]
	v_pk_mul_f32 v[100:101], v[148:149], v[100:101] op_sel_hi:[0,1]
	v_pk_mul_f32 v[80:81], v[80:81], v[96:97]
	v_pk_fma_f32 v[70:71], v[70:71], v[86:87], v[78:79]
	v_lshl_add_u64 v[78:79], v[66:67], 0, v[146:147]
	v_cvt_pk_bf16_f32 v66, v100, v101
	v_pk_mul_f32 v[98:99], v[148:149], v[98:99] op_sel_hi:[0,1]
	v_pk_mul_f32 v[102:103], v[148:149], v[102:103] op_sel_hi:[0,1]
	v_pk_mul_f32 v[104:105], v[148:149], v[104:105] op_sel_hi:[0,1]
	v_pk_fma_f32 v[72:73], v[72:73], v[88:89], v[80:81]
	v_pk_mul_f32 v[70:71], v[148:149], v[70:71] op_sel_hi:[0,1]
	v_pk_mul_f32 v[74:75], v[148:149], v[68:69] op_sel_hi:[0,1]
	v_cvt_pk_bf16_f32 v67, v98, v99
	v_cvt_pk_bf16_f32 v68, v104, v105
	v_cvt_pk_bf16_f32 v69, v102, v103
	global_store_dwordx4 v[78:79], v[66:69], off sc1
	v_pk_mul_f32 v[72:73], v[148:149], v[72:73] op_sel_hi:[0,1]
	s_nop 0
	v_cvt_pk_bf16_f32 v66, v70, v71
	v_cvt_pk_bf16_f32 v67, v72, v73
	v_cvt_pk_bf16_f32 v68, v76, v77
	v_cvt_pk_bf16_f32 v69, v74, v75
	global_store_dwordx4 v[78:79], v[66:69], off offset:64 sc1
	s_nop 1
	v_lshlrev_b32_e32 v66, 7, v157
	v_and_b32_e32 v178, 0x3e780, v66
	v_lshl_add_u64 v[70:71], v[138:139], 0, v[178:179]
	v_lshl_add_u64 v[78:79], v[140:141], 0, v[178:179]
	s_waitcnt vmcnt(2)
	v_mov_b64_e32 v[66:67], v[212:213]
	v_mov_b64_e32 v[68:69], v[214:215]
	s_nop 0
	v_mov_b64_e32 v[70:71], v[216:217]
	v_mov_b64_e32 v[72:73], v[218:219]
	s_nop 0
	v_mov_b64_e32 v[74:75], v[220:221]
	v_mov_b64_e32 v[76:77], v[222:223]
	s_nop 0
	v_mov_b64_e32 v[78:79], v[224:225]
	v_mov_b64_e32 v[80:81], v[226:227]
	v_pk_mul_f32 v[88:89], v[50:51], v[74:75]
	v_pk_mul_f32 v[86:87], v[52:53], v[76:77]
	v_pk_fma_f32 v[88:89], v[58:59], v[66:67], v[88:89] neg_lo:[0,0,1] neg_hi:[0,0,1]
	v_pk_mul_f32 v[58:59], v[58:59], v[74:75]
	v_pk_fma_f32 v[86:87], v[60:61], v[68:69], v[86:87] neg_lo:[0,0,1] neg_hi:[0,0,1]
	v_pk_mul_f32 v[60:61], v[60:61], v[76:77]
	v_pk_fma_f32 v[50:51], v[50:51], v[66:67], v[58:59]
	v_pk_fma_f32 v[52:53], v[52:53], v[68:69], v[60:61]
	v_pk_mul_f32 v[60:61], v[148:149], v[50:51] op_sel_hi:[0,1]
	v_mad_i64_i32 v[50:51], s[0:1], v157, s15, v[114:115]
	v_pk_mul_f32 v[84:85], v[54:55], v[78:79]
	v_lshl_add_u64 v[50:51], v[50:51], 0, s[28:29]
	v_pk_mul_f32 v[82:83], v[56:57], v[80:81]
	v_pk_fma_f32 v[84:85], v[62:63], v[70:71], v[84:85] neg_lo:[0,0,1] neg_hi:[0,0,1]
	v_pk_mul_f32 v[62:63], v[62:63], v[78:79]
	v_lshl_add_u64 v[50:51], v[50:51], 0, s[82:83]
	v_pk_fma_f32 v[82:83], v[64:65], v[72:73], v[82:83] neg_lo:[0,0,1] neg_hi:[0,0,1]
	v_pk_mul_f32 v[84:85], v[148:149], v[84:85] op_sel_hi:[0,1]
	v_pk_mul_f32 v[64:65], v[64:65], v[80:81]
	v_pk_fma_f32 v[54:55], v[54:55], v[70:71], v[62:63]
	v_lshl_add_u64 v[62:63], v[50:51], 0, v[146:147]
	v_cvt_pk_bf16_f32 v50, v84, v85
	v_pk_mul_f32 v[82:83], v[148:149], v[82:83] op_sel_hi:[0,1]
	v_pk_mul_f32 v[86:87], v[148:149], v[86:87] op_sel_hi:[0,1]
	v_pk_mul_f32 v[88:89], v[148:149], v[88:89] op_sel_hi:[0,1]
	v_pk_fma_f32 v[56:57], v[56:57], v[72:73], v[64:65]
	v_pk_mul_f32 v[54:55], v[148:149], v[54:55] op_sel_hi:[0,1]
	v_pk_mul_f32 v[58:59], v[148:149], v[52:53] op_sel_hi:[0,1]
	v_cvt_pk_bf16_f32 v51, v82, v83
	v_cvt_pk_bf16_f32 v52, v88, v89
	v_cvt_pk_bf16_f32 v53, v86, v87
	global_store_dwordx4 v[62:63], v[50:53], off sc1
	v_pk_mul_f32 v[56:57], v[148:149], v[56:57] op_sel_hi:[0,1]
	s_nop 0
	v_cvt_pk_bf16_f32 v50, v54, v55
	v_cvt_pk_bf16_f32 v51, v56, v57
	v_cvt_pk_bf16_f32 v52, v60, v61
	v_cvt_pk_bf16_f32 v53, v58, v59
	global_store_dwordx4 v[62:63], v[50:53], off offset:64 sc1
	s_nop 1
	v_lshlrev_b32_e32 v50, 7, v156
	v_and_b32_e32 v178, 0x3ef80, v50
	v_lshl_add_u64 v[54:55], v[138:139], 0, v[178:179]
	v_lshl_add_u64 v[62:63], v[140:141], 0, v[178:179]
	v_mov_b64_e32 v[50:51], v[228:229]
	v_mov_b64_e32 v[52:53], v[230:231]
	s_nop 0
	v_mov_b64_e32 v[54:55], v[232:233]
	v_mov_b64_e32 v[56:57], v[234:235]
	s_nop 0
	v_mov_b64_e32 v[58:59], v[236:237]
	v_mov_b64_e32 v[60:61], v[238:239]
	s_nop 0
	v_mov_b64_e32 v[62:63], v[240:241]
	v_mov_b64_e32 v[64:65], v[242:243]
	s_mov_b32 s98, 0x5000
	s_mov_b32 s99, 0
	v_lshl_add_u64 v[212:213], v[244:245], 0, s[98:99]
	global_load_dwordx4 v[212:215], v[212:213], off offset:16
	s_mov_b32 s98, 0x5000
	s_mov_b32 s99, 0
	v_lshl_add_u64 v[216:217], v[244:245], 0, s[98:99]
	global_load_dwordx4 v[216:219], v[216:217], off
	s_mov_b32 s98, 0x5000
	s_mov_b32 s99, 0
	v_lshl_add_u64 v[220:221], v[246:247], 0, s[98:99]
	global_load_dwordx4 v[220:223], v[220:221], off offset:16
	s_mov_b32 s98, 0x5000
	s_mov_b32 s99, 0
	v_lshl_add_u64 v[224:225], v[246:247], 0, s[98:99]
	global_load_dwordx4 v[224:227], v[224:225], off
	s_mov_b32 s98, 0x5800
	s_mov_b32 s99, 0
	v_lshl_add_u64 v[228:229], v[244:245], 0, s[98:99]
	global_load_dwordx4 v[228:231], v[228:229], off offset:16
	s_mov_b32 s98, 0x5800
	s_mov_b32 s99, 0
	v_lshl_add_u64 v[232:233], v[244:245], 0, s[98:99]
	global_load_dwordx4 v[232:235], v[232:233], off
	s_mov_b32 s98, 0x5800
	s_mov_b32 s99, 0
	v_lshl_add_u64 v[236:237], v[246:247], 0, s[98:99]
	global_load_dwordx4 v[236:239], v[236:237], off offset:16
	s_mov_b32 s98, 0x5800
	s_mov_b32 s99, 0
	v_lshl_add_u64 v[240:241], v[246:247], 0, s[98:99]
	global_load_dwordx4 v[240:243], v[240:241], off
	v_pk_mul_f32 v[72:73], v[34:35], v[58:59]
	v_pk_mul_f32 v[70:71], v[36:37], v[60:61]
	v_pk_fma_f32 v[72:73], v[42:43], v[50:51], v[72:73] neg_lo:[0,0,1] neg_hi:[0,0,1]
	v_pk_mul_f32 v[42:43], v[42:43], v[58:59]
	v_pk_fma_f32 v[70:71], v[44:45], v[52:53], v[70:71] neg_lo:[0,0,1] neg_hi:[0,0,1]
	v_pk_mul_f32 v[44:45], v[44:45], v[60:61]
	v_pk_fma_f32 v[34:35], v[34:35], v[50:51], v[42:43]
	v_pk_fma_f32 v[36:37], v[36:37], v[52:53], v[44:45]
	v_pk_mul_f32 v[44:45], v[148:149], v[34:35] op_sel_hi:[0,1]
	v_mad_i64_i32 v[34:35], s[0:1], v156, s15, v[114:115]
	v_pk_mul_f32 v[68:69], v[38:39], v[62:63]
	v_lshl_add_u64 v[34:35], v[34:35], 0, s[28:29]
	v_pk_mul_f32 v[66:67], v[40:41], v[64:65]
	v_pk_fma_f32 v[68:69], v[46:47], v[54:55], v[68:69] neg_lo:[0,0,1] neg_hi:[0,0,1]
	v_pk_mul_f32 v[46:47], v[46:47], v[62:63]
	v_lshl_add_u64 v[34:35], v[34:35], 0, s[82:83]
	v_pk_fma_f32 v[66:67], v[48:49], v[56:57], v[66:67] neg_lo:[0,0,1] neg_hi:[0,0,1]
	v_pk_mul_f32 v[68:69], v[148:149], v[68:69] op_sel_hi:[0,1]
	v_pk_mul_f32 v[48:49], v[48:49], v[64:65]
	v_pk_fma_f32 v[38:39], v[38:39], v[54:55], v[46:47]
	v_lshl_add_u64 v[46:47], v[34:35], 0, v[146:147]
	v_cvt_pk_bf16_f32 v34, v68, v69
	v_pk_mul_f32 v[66:67], v[148:149], v[66:67] op_sel_hi:[0,1]
	v_pk_mul_f32 v[70:71], v[148:149], v[70:71] op_sel_hi:[0,1]
	v_pk_mul_f32 v[72:73], v[148:149], v[72:73] op_sel_hi:[0,1]
	v_pk_fma_f32 v[40:41], v[40:41], v[56:57], v[48:49]
	v_pk_mul_f32 v[38:39], v[148:149], v[38:39] op_sel_hi:[0,1]
	v_pk_mul_f32 v[42:43], v[148:149], v[36:37] op_sel_hi:[0,1]
	v_cvt_pk_bf16_f32 v35, v66, v67
	v_cvt_pk_bf16_f32 v36, v72, v73
	v_cvt_pk_bf16_f32 v37, v70, v71
	global_store_dwordx4 v[46:47], v[34:37], off sc1
	v_pk_mul_f32 v[40:41], v[148:149], v[40:41] op_sel_hi:[0,1]
	s_nop 0
	v_cvt_pk_bf16_f32 v34, v38, v39
	v_cvt_pk_bf16_f32 v35, v40, v41
	v_cvt_pk_bf16_f32 v36, v44, v45
	v_cvt_pk_bf16_f32 v37, v42, v43
	global_store_dwordx4 v[46:47], v[34:37], off offset:64 sc1
	s_nop 1
	v_lshlrev_b32_e32 v34, 7, v155
	v_and_b32_e32 v178, 0x3f780, v34
	v_lshl_add_u64 v[38:39], v[138:139], 0, v[178:179]
	v_lshl_add_u64 v[46:47], v[140:141], 0, v[178:179]
	s_waitcnt vmcnt(2)
	v_mov_b64_e32 v[34:35], v[212:213]
	v_mov_b64_e32 v[36:37], v[214:215]
	s_nop 0
	v_mov_b64_e32 v[38:39], v[216:217]
	v_mov_b64_e32 v[40:41], v[218:219]
	s_nop 0
	v_mov_b64_e32 v[42:43], v[220:221]
	v_mov_b64_e32 v[44:45], v[222:223]
	s_nop 0
	v_mov_b64_e32 v[46:47], v[224:225]
	v_mov_b64_e32 v[48:49], v[226:227]
	v_pk_mul_f32 v[56:57], v[18:19], v[42:43]
	v_pk_mul_f32 v[54:55], v[20:21], v[44:45]
	v_pk_fma_f32 v[56:57], v[26:27], v[34:35], v[56:57] neg_lo:[0,0,1] neg_hi:[0,0,1]
	v_pk_mul_f32 v[26:27], v[26:27], v[42:43]
	v_pk_fma_f32 v[54:55], v[28:29], v[36:37], v[54:55] neg_lo:[0,0,1] neg_hi:[0,0,1]
	v_pk_mul_f32 v[28:29], v[28:29], v[44:45]
	v_pk_fma_f32 v[18:19], v[18:19], v[34:35], v[26:27]
	v_pk_fma_f32 v[20:21], v[20:21], v[36:37], v[28:29]
	v_pk_mul_f32 v[28:29], v[148:149], v[18:19] op_sel_hi:[0,1]
	v_mad_i64_i32 v[18:19], s[0:1], v155, s15, v[114:115]
	v_pk_mul_f32 v[52:53], v[22:23], v[46:47]
	v_lshl_add_u64 v[18:19], v[18:19], 0, s[28:29]
	v_pk_mul_f32 v[50:51], v[24:25], v[48:49]
	v_pk_fma_f32 v[52:53], v[30:31], v[38:39], v[52:53] neg_lo:[0,0,1] neg_hi:[0,0,1]
	v_pk_mul_f32 v[30:31], v[30:31], v[46:47]
	v_lshl_add_u64 v[18:19], v[18:19], 0, s[82:83]
	v_pk_fma_f32 v[50:51], v[32:33], v[40:41], v[50:51] neg_lo:[0,0,1] neg_hi:[0,0,1]
	v_pk_mul_f32 v[52:53], v[148:149], v[52:53] op_sel_hi:[0,1]
	v_pk_mul_f32 v[32:33], v[32:33], v[48:49]
	v_pk_fma_f32 v[22:23], v[22:23], v[38:39], v[30:31]
	v_lshl_add_u64 v[30:31], v[18:19], 0, v[146:147]
	v_cvt_pk_bf16_f32 v18, v52, v53
	v_pk_mul_f32 v[50:51], v[148:149], v[50:51] op_sel_hi:[0,1]
	v_pk_mul_f32 v[54:55], v[148:149], v[54:55] op_sel_hi:[0,1]
	v_pk_mul_f32 v[56:57], v[148:149], v[56:57] op_sel_hi:[0,1]
	v_pk_fma_f32 v[24:25], v[24:25], v[40:41], v[32:33]
	v_pk_mul_f32 v[22:23], v[148:149], v[22:23] op_sel_hi:[0,1]
	v_pk_mul_f32 v[26:27], v[148:149], v[20:21] op_sel_hi:[0,1]
	v_cvt_pk_bf16_f32 v19, v50, v51
	v_cvt_pk_bf16_f32 v20, v56, v57
	v_cvt_pk_bf16_f32 v21, v54, v55
	global_store_dwordx4 v[30:31], v[18:21], off sc1
	v_pk_mul_f32 v[24:25], v[148:149], v[24:25] op_sel_hi:[0,1]
	s_nop 0
	v_cvt_pk_bf16_f32 v18, v22, v23
	v_cvt_pk_bf16_f32 v19, v24, v25
	v_cvt_pk_bf16_f32 v20, v28, v29
	v_cvt_pk_bf16_f32 v21, v26, v27
	global_store_dwordx4 v[30:31], v[18:21], off offset:64 sc1
	s_nop 1
	v_lshlrev_b32_e32 v18, 7, v154
	v_and_b32_e32 v178, 0x3ff80, v18
	v_lshl_add_u64 v[18:19], v[138:139], 0, v[178:179]
	v_mov_b64_e32 v[22:23], v[228:229]
	v_mov_b64_e32 v[24:25], v[230:231]
	v_mov_b64_e32 v[26:27], v[232:233]
	v_mov_b64_e32 v[28:29], v[234:235]
	v_lshl_add_u64 v[18:19], v[140:141], 0, v[178:179]
	v_mov_b64_e32 v[30:31], v[236:237]
	v_mov_b64_e32 v[32:33], v[238:239]
	v_mov_b64_e32 v[34:35], v[240:241]
	v_mov_b64_e32 v[36:37], v[242:243]
	v_pk_mul_f32 v[40:41], v[2:3], v[30:31]
	v_pk_mul_f32 v[20:21], v[6:7], v[34:35]
	v_pk_fma_f32 v[40:41], v[10:11], v[22:23], v[40:41] neg_lo:[0,0,1] neg_hi:[0,0,1]
	v_pk_fma_f32 v[20:21], v[14:15], v[26:27], v[20:21] neg_lo:[0,0,1] neg_hi:[0,0,1]
	v_pk_mul_f32 v[10:11], v[10:11], v[30:31]
	v_pk_mul_f32 v[38:39], v[148:149], v[20:21] op_sel_hi:[0,1]
	v_pk_mul_f32 v[20:21], v[4:5], v[32:33]
	v_pk_fma_f32 v[10:11], v[2:3], v[22:23], v[10:11]
	v_pk_fma_f32 v[20:21], v[12:13], v[24:25], v[20:21] neg_lo:[0,0,1] neg_hi:[0,0,1]
	v_pk_mul_f32 v[12:13], v[12:13], v[32:33]
	v_pk_mul_f32 v[18:19], v[8:9], v[36:37]
	v_pk_fma_f32 v[4:5], v[4:5], v[24:25], v[12:13]
	v_pk_fma_f32 v[18:19], v[16:17], v[28:29], v[18:19] neg_lo:[0,0,1] neg_hi:[0,0,1]
	v_pk_mul_f32 v[2:3], v[148:149], v[4:5] op_sel_hi:[0,1]
	v_pk_mul_f32 v[4:5], v[148:149], v[10:11] op_sel_hi:[0,1]
	v_mad_i64_i32 v[10:11], s[0:1], v154, s15, v[114:115]
	v_pk_mul_f32 v[16:17], v[16:17], v[36:37]
	v_pk_mul_f32 v[14:15], v[14:15], v[34:35]
	v_lshl_add_u64 v[10:11], v[10:11], 0, s[28:29]
	v_pk_fma_f32 v[8:9], v[8:9], v[28:29], v[16:17]
	v_pk_fma_f32 v[14:15], v[6:7], v[26:27], v[14:15]
	v_lshl_add_u64 v[10:11], v[10:11], 0, s[82:83]
	v_pk_mul_f32 v[18:19], v[148:149], v[18:19] op_sel_hi:[0,1]
	v_pk_mul_f32 v[6:7], v[148:149], v[8:9] op_sel_hi:[0,1]
	v_pk_mul_f32 v[8:9], v[148:149], v[14:15] op_sel_hi:[0,1]
	v_lshl_add_u64 v[14:15], v[10:11], 0, v[146:147]
	v_cvt_pk_bf16_f32 v10, v38, v39
	v_cvt_pk_bf16_f32 v11, v18, v19
	v_pk_mul_f32 v[20:21], v[148:149], v[20:21] op_sel_hi:[0,1]
	v_pk_mul_f32 v[40:41], v[148:149], v[40:41] op_sel_hi:[0,1]
	v_cvt_pk_bf16_f32 v12, v40, v41
	v_cvt_pk_bf16_f32 v13, v20, v21
	global_store_dwordx4 v[14:15], v[10:13], off sc1
	v_cvt_pk_bf16_f32 v8, v8, v9
	v_cvt_pk_bf16_f32 v9, v6, v7
	s_nop 1
	v_cvt_pk_bf16_f32 v10, v4, v5
	v_cvt_pk_bf16_f32 v11, v2, v3
	global_store_dwordx4 v[14:15], v[8:11], off offset:64 sc1
	s_andn2_b64 vcc, exec, s[4:5]
	s_mov_b64 s[0:1], -1
	s_cbranch_vccnz .LBB0_211
